# FFN-in epilogue body regenerated with packed f32 ops and nop-free interleave ((a*b)*sigmoid association)
# baseline (speedup 1.0000x reference)
; __device__ __forceinline__ float row_rstd(const float* ssp, int row, int fq) {
;     const f32x4 t = *((const f32x4*)(ssp + (size_t)row * 16) + fq); float s = (t[0] + t[1]) + (t[2] + t[3]); s += __shfl_xor(s, 16); s += __shfl_xor(s, 32); return rsqrtf(s * (1.0f / DM) + EPS); }
;     __device__ __forceinline__ void operator()(const f32x4 (&acc)[2][2][4][2], const Unit& u, int wr, int wc, int fr, int fq) const {
;     ...
;         float rx[2][4];
; #pragma unroll
;         for (int ai = 0; ai < 2; ++ai)
; #pragma unroll
;             for (int m = 0; m < 4; ++m) rx[ai][m] = row_rstd(ssp, row0 + ai * HALF + m * 16, fq);
; #pragma unroll
;         for (int ai = 0; ai < 2; ++ai)
; #pragma unroll
;             for (int m = 0; m < 4; ++m) { f32x4 o[2];
; #pragma unroll
;                 for (int n = 0; n < 2; ++n) { const f32x4 a = acc[ai][0][m][n] * rx[ai][m], b = acc[ai][1][m][n] * rx[ai][m];
.LBB0_580:
	v_and_b32_e32 v129, 64, v229
	v_xor_b32_e32 v128, 16, v229
	v_add_u32_e32 v129, 64, v129
	v_cmp_lt_i32_e32 vcc, v128, v129
	v_lshl_add_u32 v130, s42, 8, v147
	v_ashrrev_i32_e32 v131, 31, v130
	v_cndmask_b32_e32 v128, v229, v128, vcc
	v_lshlrev_b32_e32 v162, 2, v128
	v_xor_b32_e32 v128, 32, v229
	v_cmp_lt_i32_e32 vcc, v128, v129
	s_mov_b32 s4, 0x358637bd
	s_ashr_i32 s29, s42, 4
	v_cndmask_b32_e32 v128, v229, v128, vcc
	v_lshlrev_b32_e32 v157, 2, v128
	v_lshlrev_b64 v[128:129], 6, v[130:131]
	v_lshl_add_u64 v[128:129], v[140:141], 0, v[128:129]
	global_load_dwordx4 v[170:173], v[128:129], off
	global_load_dwordx4 v[174:177], v[128:129], off offset:1024
	global_load_dwordx4 v[178:181], v[128:129], off offset:2048
	global_load_dwordx4 v[182:185], v[128:129], off offset:3072
	v_add_co_u32_e32 v206, vcc, s82, v128
	s_nop 1
	v_addc_co_u32_e32 v207, vcc, 0, v129, vcc
	global_load_dwordx4 v[186:189], v[206:207], off
	global_load_dwordx4 v[194:197], v[206:207], off offset:1024
	global_load_dwordx4 v[198:201], v[206:207], off offset:2048
	global_load_dwordx4 v[202:205], v[206:207], off offset:3072
	v_and_b32_e32 v155, 0xfcf, v130
	s_mul_hi_i32 s27, s29, 0x1c00000
	s_mul_i32 s29, s29, 0x1c00000
	s_add_u32 s10, s56, s29
	s_addc_u32 s11, s57, s27
	s_waitcnt vmcnt(7)
	v_mov_b32_e32 v164, v171
	v_mov_b32_e32 v165, v172
	v_mov_b32_e32 v171, v173
	v_pk_add_f32 v[164:165], v[164:165], v[170:171]
	s_waitcnt vmcnt(6)
	v_mov_b32_e32 v166, v175
	v_mov_b32_e32 v167, v176
	v_mov_b32_e32 v175, v177
	v_pk_add_f32 v[158:159], v[166:167], v[174:175]
	v_mov_b32_e32 v161, v164
	v_mov_b32_e32 v160, v158
	v_mov_b32_e32 v164, v159
	v_pk_add_f32 v[158:159], v[160:161], v[164:165]
	ds_bpermute_b32 v161, v162, v159
	ds_bpermute_b32 v160, v162, v158
	s_waitcnt lgkmcnt(0)
	v_pk_add_f32 v[158:159], v[158:159], v[160:161]
	ds_bpermute_b32 v161, v157, v159
	ds_bpermute_b32 v160, v157, v158
	s_waitcnt lgkmcnt(0)
	v_pk_add_f32 v[160:161], v[158:159], v[160:161]
	v_mov_b64_e32 v[158:159], s[4:5]
	v_pk_fma_f32 v[160:161], v[160:161], s[38:39], v[158:159] op_sel_hi:[1,0,0]
	s_nop 0
	v_mul_f32_e32 v131, 0x4b800000, v161
	v_cmp_gt_f32_e64 s[42:43], s99, v161
	v_cmp_gt_f32_e32 vcc, s99, v160
	s_nop 0
	v_cndmask_b32_e64 v131, v161, v131, s[42:43]
	v_rsq_f32_e32 v131, v131
	s_nop 0
	v_mul_f32_e32 v146, 0x45800000, v131
	v_cndmask_b32_e64 v156, v131, v146, s[42:43]
	v_mul_f32_e32 v131, 0x4b800000, v160
	v_cndmask_b32_e32 v131, v160, v131, vcc
	v_rsq_f32_e32 v131, v131
	v_pk_mul_f32 v[124:125], v[124:125], v[156:157] op_sel_hi:[1,0]
	v_pk_mul_f32 v[120:121], v[120:121], v[156:157] op_sel_hi:[1,0]
	v_mul_f32_e32 v146, 0x45800000, v131
	v_cndmask_b32_e32 v154, v131, v146, vcc
	v_pk_mul_f32 v[122:123], v[122:123], v[156:157] op_sel_hi:[1,0]
	v_pk_mul_f32 v[116:117], v[116:117], v[156:157] op_sel_hi:[1,0]
	v_pk_mul_f32 v[112:113], v[112:113], v[156:157] op_sel_hi:[1,0]
	v_pk_mul_f32 v[114:115], v[114:115], v[156:157] op_sel_hi:[1,0]
	v_pk_mul_f32 v[108:109], v[108:109], v[154:155] op_sel_hi:[1,0]
	v_pk_mul_f32 v[104:105], v[104:105], v[154:155] op_sel_hi:[1,0]
	v_pk_mul_f32 v[106:107], v[106:107], v[154:155] op_sel_hi:[1,0]
	v_pk_mul_f32 v[100:101], v[100:101], v[154:155] op_sel_hi:[1,0]
	v_pk_mul_f32 v[96:97], v[96:97], v[154:155] op_sel_hi:[1,0]
	v_pk_mul_f32 v[98:99], v[98:99], v[154:155] op_sel_hi:[1,0]
	s_waitcnt vmcnt(5)
	v_mov_b32_e32 v160, v179
	v_mov_b32_e32 v161, v180
	v_mov_b32_e32 v179, v181
	v_pk_add_f32 v[160:161], v[160:161], v[178:179]
	s_waitcnt vmcnt(4)
	v_mov_b32_e32 v130, v183
	v_mov_b32_e32 v131, v184
	v_mov_b32_e32 v183, v185
	v_pk_add_f32 v[130:131], v[130:131], v[182:183]
	v_mov_b32_e32 v165, v160
	v_mov_b32_e32 v164, v130
	v_mov_b32_e32 v160, v131
	v_pk_add_f32 v[130:131], v[164:165], v[160:161]
	ds_bpermute_b32 v161, v162, v131
	ds_bpermute_b32 v160, v162, v130
	s_waitcnt lgkmcnt(0)
	v_pk_add_f32 v[130:131], v[130:131], v[160:161]
	ds_bpermute_b32 v161, v157, v131
	ds_bpermute_b32 v160, v157, v130
	s_waitcnt lgkmcnt(0)
	v_pk_add_f32 v[130:131], v[130:131], v[160:161]
	s_nop 0
	v_pk_fma_f32 v[130:131], v[130:131], s[38:39], v[158:159] op_sel_hi:[1,0,0]
	s_nop 0
	v_mul_f32_e32 v146, 0x4b800000, v131
	v_cmp_gt_f32_e64 s[42:43], s99, v131
	v_cmp_gt_f32_e32 vcc, s99, v130
	s_nop 0
	v_cndmask_b32_e64 v131, v131, v146, s[42:43]
	v_rsq_f32_e32 v131, v131
	s_nop 0
	v_mul_f32_e32 v146, 0x45800000, v131
	v_cndmask_b32_e64 v152, v131, v146, s[42:43]
	v_mul_f32_e32 v131, 0x4b800000, v130
	v_cndmask_b32_e32 v130, v130, v131, vcc
	v_rsq_f32_e32 v130, v130
	v_pk_mul_f32 v[92:93], v[92:93], v[152:153] op_sel_hi:[1,0]
	v_pk_mul_f32 v[88:89], v[88:89], v[152:153] op_sel_hi:[1,0]
	v_pk_mul_f32 v[90:91], v[90:91], v[152:153] op_sel_hi:[1,0]
	v_mul_f32_e32 v131, 0x45800000, v130
	v_cndmask_b32_e32 v150, v130, v131, vcc
	v_pk_mul_f32 v[84:85], v[84:85], v[152:153] op_sel_hi:[1,0]
	v_pk_mul_f32 v[80:81], v[80:81], v[152:153] op_sel_hi:[1,0]
	v_pk_mul_f32 v[82:83], v[82:83], v[152:153] op_sel_hi:[1,0]
	v_pk_mul_f32 v[76:77], v[76:77], v[150:151] op_sel_hi:[1,0]
	v_pk_mul_f32 v[72:73], v[72:73], v[150:151] op_sel_hi:[1,0]
	v_pk_mul_f32 v[74:75], v[74:75], v[150:151] op_sel_hi:[1,0]
	v_pk_mul_f32 v[68:69], v[68:69], v[150:151] op_sel_hi:[1,0]
	v_pk_mul_f32 v[64:65], v[64:65], v[150:151] op_sel_hi:[1,0]
	v_pk_mul_f32 v[66:67], v[66:67], v[150:151] op_sel_hi:[1,0]
	s_waitcnt vmcnt(3)
	v_mov_b32_e32 v130, v187
	v_mov_b32_e32 v131, v188
	v_mov_b32_e32 v187, v189
	v_pk_add_f32 v[130:131], v[130:131], v[186:187]
	s_waitcnt vmcnt(2)
; __device__ __forceinline__ u32x4 pack8(const f32x4& a, const f32x4& b) { u32x4 w; w.x = pk2(a[0], a[1]); w.y = pk2(a[2], a[3]); w.z = pk2(b[0], b[1]); w.w = pk2(b[2], b[3]); return w; }
; __device__ __forceinline__ float sigm(float x) { return __builtin_amdgcn_rcpf(1.0f + __builtin_amdgcn_exp2f(x * -1.4426950408889634f)); }
;     __device__ __forceinline__ void operator()(const f32x4 (&acc)[2][2][4][2], const Unit& u, int wr, int wc, int fr, int fq) const {
;     ...
; #pragma unroll
;         for (int ai = 0; ai < 2; ++ai)
; #pragma unroll
;             for (int m = 0; m < 4; ++m) { f32x4 o[2];
; #pragma unroll
;                 for (int n = 0; n < 2; ++n) { const f32x4 a = acc[ai][0][m][n] * rx[ai][m], b = acc[ai][1][m][n] * rx[ai][m];
; #pragma unroll
;                     for (int e = 0; e < 4; ++e) o[n][e] = a[e] * sigm(a[e]) * b[e]; }
;                 *(u32x4*)(H + (size_t)(lrow0 + ai * HALF + m * 16) * DFF + col0) = pack8(o[0], o[1]); asm volatile("" ::: "memory"); }
	v_mov_b32_e32 v160, v195
	v_mov_b32_e32 v161, v196
	v_mov_b32_e32 v195, v197
	v_pk_add_f32 v[160:161], v[160:161], v[194:195]
	v_mov_b32_e32 v165, v130
	v_mov_b32_e32 v164, v160
	v_mov_b32_e32 v130, v161
	v_pk_add_f32 v[130:131], v[164:165], v[130:131]
	ds_bpermute_b32 v161, v162, v131
	ds_bpermute_b32 v160, v162, v130
	s_waitcnt lgkmcnt(0)
	v_pk_add_f32 v[130:131], v[130:131], v[160:161]
	ds_bpermute_b32 v161, v157, v131
	ds_bpermute_b32 v160, v157, v130
	s_waitcnt lgkmcnt(0)
	v_pk_add_f32 v[130:131], v[130:131], v[160:161]
	s_nop 0
	v_pk_fma_f32 v[130:131], v[130:131], s[38:39], v[158:159] op_sel_hi:[1,0,0]
	s_nop 0
	v_mul_f32_e32 v146, 0x4b800000, v131
	v_cmp_gt_f32_e64 s[42:43], s99, v131
	v_cmp_gt_f32_e32 vcc, s99, v130
	s_nop 0
	v_cndmask_b32_e64 v131, v131, v146, s[42:43]
	v_rsq_f32_e32 v131, v131
	s_nop 0
	v_mul_f32_e32 v146, 0x45800000, v131
	v_cndmask_b32_e64 v148, v131, v146, s[42:43]
	v_mul_f32_e32 v131, 0x4b800000, v130
	v_cndmask_b32_e32 v130, v130, v131, vcc
	v_rsq_f32_e32 v130, v130
	v_pk_mul_f32 v[60:61], v[60:61], v[148:149] op_sel_hi:[1,0]
	v_pk_mul_f32 v[56:57], v[56:57], v[148:149] op_sel_hi:[1,0]
	v_pk_mul_f32 v[58:59], v[58:59], v[148:149] op_sel_hi:[1,0]
	v_mul_f32_e32 v131, 0x45800000, v130
	v_cndmask_b32_e32 v146, v130, v131, vcc
	v_pk_mul_f32 v[52:53], v[52:53], v[148:149] op_sel_hi:[1,0]
	v_pk_mul_f32 v[48:49], v[48:49], v[148:149] op_sel_hi:[1,0]
	v_pk_mul_f32 v[50:51], v[50:51], v[148:149] op_sel_hi:[1,0]
	v_pk_mul_f32 v[44:45], v[44:45], v[146:147] op_sel_hi:[1,0]
	v_pk_mul_f32 v[40:41], v[40:41], v[146:147] op_sel_hi:[1,0]
	v_pk_mul_f32 v[42:43], v[42:43], v[146:147] op_sel_hi:[1,0]
	v_pk_mul_f32 v[36:37], v[36:37], v[146:147] op_sel_hi:[1,0]
	v_pk_mul_f32 v[32:33], v[32:33], v[146:147] op_sel_hi:[1,0]
	v_pk_mul_f32 v[34:35], v[34:35], v[146:147] op_sel_hi:[1,0]
	s_waitcnt vmcnt(1)
	v_mov_b32_e32 v130, v199
	v_mov_b32_e32 v131, v200
	v_mov_b32_e32 v199, v201
	v_pk_add_f32 v[160:161], v[130:131], v[198:199]
	s_waitcnt vmcnt(0)
	v_mov_b32_e32 v164, v203
	v_mov_b32_e32 v165, v204
	v_mov_b32_e32 v203, v205
	v_pk_add_f32 v[128:129], v[164:165], v[202:203]
	v_mov_b32_e32 v131, v160
	v_mov_b32_e32 v130, v128
	v_mov_b32_e32 v160, v129
	v_pk_add_f32 v[128:129], v[130:131], v[160:161]
	ds_bpermute_b32 v131, v162, v129
	ds_bpermute_b32 v130, v162, v128
	s_waitcnt lgkmcnt(0)
	v_pk_add_f32 v[128:129], v[128:129], v[130:131]
	ds_bpermute_b32 v131, v157, v129
	ds_bpermute_b32 v130, v157, v128
	s_waitcnt lgkmcnt(0)
	v_pk_add_f32 v[128:129], v[128:129], v[130:131]
	s_nop 0
	v_pk_fma_f32 v[128:129], v[128:129], s[38:39], v[158:159] op_sel_hi:[1,0,0]
	v_lshl_or_b32 v158, s59, 7, v151
	v_mul_f32_e32 v130, 0x4b800000, v129
	v_cmp_gt_f32_e64 s[42:43], s99, v129
	v_cmp_gt_f32_e32 vcc, s99, v128
	v_ashrrev_i32_e32 v159, 31, v158
	v_cndmask_b32_e64 v129, v129, v130, s[42:43]
	v_rsq_f32_e32 v129, v129
	v_lshl_add_u64 v[158:159], v[158:159], 1, s[10:11]
	v_mul_f32_e32 v130, 0x45800000, v129
	v_cndmask_b32_e64 v130, v129, v130, s[42:43]
	v_mul_f32_e32 v129, 0x4b800000, v128
	v_cndmask_b32_e32 v128, v128, v129, vcc
	v_rsq_f32_e32 v128, v128
	v_pk_mul_f32 v[28:29], v[28:29], v[130:131] op_sel_hi:[1,0]
	v_pk_mul_f32 v[24:25], v[24:25], v[130:131] op_sel_hi:[1,0]
	v_pk_mul_f32 v[26:27], v[26:27], v[130:131] op_sel_hi:[1,0]
	v_mul_f32_e32 v129, 0x45800000, v128
	v_cndmask_b32_e32 v128, v128, v129, vcc
	s_mov_b64 s[42:43], -1
	v_pk_mul_f32 v[126:127], v[126:127], v[156:157] op_sel_hi:[1,0]
	v_pk_mul_f32 v[118:119], v[118:119], v[156:157] op_sel_hi:[1,0]
	v_pk_mul_f32 v[110:111], v[110:111], v[154:155] op_sel_hi:[1,0]
	v_pk_mul_f32 v[102:103], v[102:103], v[154:155] op_sel_hi:[1,0]
	v_pk_mul_f32 v[94:95], v[94:95], v[152:153] op_sel_hi:[1,0]
	v_pk_mul_f32 v[86:87], v[86:87], v[152:153] op_sel_hi:[1,0]
	v_pk_mul_f32 v[78:79], v[78:79], v[150:151] op_sel_hi:[1,0]
	v_pk_mul_f32 v[70:71], v[70:71], v[150:151] op_sel_hi:[1,0]
	v_pk_mul_f32 v[62:63], v[62:63], v[148:149] op_sel_hi:[1,0]
	v_pk_mul_f32 v[54:55], v[54:55], v[148:149] op_sel_hi:[1,0]
	v_pk_mul_f32 v[46:47], v[46:47], v[146:147] op_sel_hi:[1,0]
	v_pk_mul_f32 v[38:39], v[38:39], v[146:147] op_sel_hi:[1,0]
	v_pk_mul_f32 v[30:31], v[30:31], v[130:131] op_sel_hi:[1,0]
	v_pk_mul_f32 v[22:23], v[22:23], v[130:131] op_sel_hi:[1,0]
	v_pk_mul_f32 v[20:21], v[20:21], v[130:131] op_sel_hi:[1,0]
	v_pk_mul_f32 v[18:19], v[18:19], v[130:131] op_sel_hi:[1,0]
	v_pk_mul_f32 v[16:17], v[16:17], v[130:131] op_sel_hi:[1,0]
	v_pk_mul_f32 v[14:15], v[14:15], v[128:129] op_sel_hi:[1,0]
	v_pk_mul_f32 v[12:13], v[12:13], v[128:129] op_sel_hi:[1,0]
	v_pk_mul_f32 v[10:11], v[10:11], v[128:129] op_sel_hi:[1,0]
	v_pk_mul_f32 v[8:9], v[8:9], v[128:129] op_sel_hi:[1,0]
	v_pk_mul_f32 v[6:7], v[6:7], v[128:129] op_sel_hi:[1,0]
	v_pk_mul_f32 v[4:5], v[4:5], v[128:129] op_sel_hi:[1,0]
	v_pk_mul_f32 v[2:3], v[2:3], v[128:129] op_sel_hi:[1,0]
	v_pk_mul_f32 v[0:1], v[0:1], v[128:129] op_sel_hi:[1,0]
	v_mul_u32_u24_e32 v208, 0xb00, v155
	v_mov_b32_e32 v209, v193
	v_mov_b32_e32 v224, 0xbfb8aa3b
	v_mov_b32_e32 v225, 0xbfb8aa3b
	v_lshlrev_b32_e32 v208, 1, v208
	v_mov_b32_e32 v214, 1.0
	v_mov_b32_e32 v215, 1.0
	v_lshl_add_u64 v[210:211], v[158:159], 0, v[208:209]
	v_pk_mul_f32 v[216:217], v[124:125], v[224:225]
	v_pk_mul_f32 v[218:219], v[126:127], v[224:225]
	v_pk_mul_f32 v[220:221], v[116:117], v[224:225]
	v_pk_mul_f32 v[222:223], v[118:119], v[224:225]
	v_exp_f32_e32 v216, v216
	v_exp_f32_e32 v217, v217
	v_exp_f32_e32 v218, v218
	v_exp_f32_e32 v219, v219
	v_exp_f32_e32 v220, v220
	v_exp_f32_e32 v221, v221
	v_exp_f32_e32 v222, v222
	v_exp_f32_e32 v223, v223
	v_pk_mul_f32 v[120:121], v[124:125], v[120:121]
; __device__ __forceinline__ u32x4 pack8(const f32x4& a, const f32x4& b) { u32x4 w; w.x = pk2(a[0], a[1]); w.y = pk2(a[2], a[3]); w.z = pk2(b[0], b[1]); w.w = pk2(b[2], b[3]); return w; }
; __device__ __forceinline__ float sigm(float x) { return __builtin_amdgcn_rcpf(1.0f + __builtin_amdgcn_exp2f(x * -1.4426950408889634f)); }
;     __device__ __forceinline__ void operator()(const f32x4 (&acc)[2][2][4][2], const Unit& u, int wr, int wc, int fr, int fq) const {
;     ...
; #pragma unroll
;         for (int ai = 0; ai < 2; ++ai)
; #pragma unroll
;             for (int m = 0; m < 4; ++m) { f32x4 o[2];
; #pragma unroll
;                 for (int n = 0; n < 2; ++n) { const f32x4 a = acc[ai][0][m][n] * rx[ai][m], b = acc[ai][1][m][n] * rx[ai][m];
; #pragma unroll
;                     for (int e = 0; e < 4; ++e) o[n][e] = a[e] * sigm(a[e]) * b[e]; }
;                 *(u32x4*)(H + (size_t)(lrow0 + ai * HALF + m * 16) * DFF + col0) = pack8(o[0], o[1]); asm volatile("" ::: "memory"); }
	v_pk_mul_f32 v[122:123], v[126:127], v[122:123]
	v_pk_mul_f32 v[112:113], v[116:117], v[112:113]
	v_pk_mul_f32 v[114:115], v[118:119], v[114:115]
	v_pk_add_f32 v[216:217], v[216:217], v[214:215]
	v_pk_add_f32 v[218:219], v[218:219], v[214:215]
	v_pk_add_f32 v[220:221], v[220:221], v[214:215]
	v_pk_add_f32 v[222:223], v[222:223], v[214:215]
	v_rcp_f32_e32 v216, v216
	v_rcp_f32_e32 v217, v217
	v_rcp_f32_e32 v218, v218
	v_rcp_f32_e32 v219, v219
	v_rcp_f32_e32 v220, v220
	v_rcp_f32_e32 v221, v221
	v_rcp_f32_e32 v222, v222
	v_rcp_f32_e32 v223, v223
	s_nop 0
	v_pk_mul_f32 v[120:121], v[120:121], v[216:217]
	v_pk_mul_f32 v[122:123], v[122:123], v[218:219]
	v_pk_mul_f32 v[112:113], v[112:113], v[220:221]
	v_pk_mul_f32 v[114:115], v[114:115], v[222:223]
	v_cvt_pk_bf16_f32 v124, v120, v121
	v_cvt_pk_bf16_f32 v125, v122, v123
	v_cvt_pk_bf16_f32 v126, v112, v113
	v_cvt_pk_bf16_f32 v127, v114, v115
	global_store_dwordx4 v[210:211], v[124:127], off
	v_pk_mul_f32 v[216:217], v[108:109], v[224:225]
	v_pk_mul_f32 v[218:219], v[110:111], v[224:225]
	v_pk_mul_f32 v[220:221], v[100:101], v[224:225]
	v_pk_mul_f32 v[222:223], v[102:103], v[224:225]
	v_exp_f32_e32 v216, v216
	v_exp_f32_e32 v217, v217
	v_exp_f32_e32 v218, v218
	v_exp_f32_e32 v219, v219
	v_exp_f32_e32 v220, v220
	v_exp_f32_e32 v221, v221
	v_exp_f32_e32 v222, v222
	v_exp_f32_e32 v223, v223
	v_pk_mul_f32 v[104:105], v[108:109], v[104:105]
	v_pk_mul_f32 v[106:107], v[110:111], v[106:107]
	v_pk_mul_f32 v[96:97], v[100:101], v[96:97]
	v_pk_mul_f32 v[98:99], v[102:103], v[98:99]
	v_pk_add_f32 v[216:217], v[216:217], v[214:215]
	v_pk_add_f32 v[218:219], v[218:219], v[214:215]
	v_pk_add_f32 v[220:221], v[220:221], v[214:215]
	v_pk_add_f32 v[222:223], v[222:223], v[214:215]
	v_rcp_f32_e32 v216, v216
	v_rcp_f32_e32 v217, v217
	v_rcp_f32_e32 v218, v218
	v_rcp_f32_e32 v219, v219
	v_rcp_f32_e32 v220, v220
	v_rcp_f32_e32 v221, v221
	v_rcp_f32_e32 v222, v222
	v_rcp_f32_e32 v223, v223
	s_mov_b64 s[10:11], 0x16000
	v_lshl_add_u64 v[208:209], v[210:211], 0, s[10:11]
	v_pk_mul_f32 v[104:105], v[104:105], v[216:217]
	v_pk_mul_f32 v[106:107], v[106:107], v[218:219]
	v_pk_mul_f32 v[96:97], v[96:97], v[220:221]
	v_pk_mul_f32 v[98:99], v[98:99], v[222:223]
	v_cvt_pk_bf16_f32 v108, v104, v105
	v_cvt_pk_bf16_f32 v109, v106, v107
	v_cvt_pk_bf16_f32 v110, v96, v97
	v_cvt_pk_bf16_f32 v111, v98, v99
	global_store_dwordx4 v[208:209], v[108:111], off
	v_pk_mul_f32 v[216:217], v[92:93], v[224:225]
	v_pk_mul_f32 v[218:219], v[94:95], v[224:225]
	v_pk_mul_f32 v[220:221], v[84:85], v[224:225]
	v_pk_mul_f32 v[222:223], v[86:87], v[224:225]
	v_exp_f32_e32 v216, v216
	v_exp_f32_e32 v217, v217
	v_exp_f32_e32 v218, v218
	v_exp_f32_e32 v219, v219
	v_exp_f32_e32 v220, v220
	v_exp_f32_e32 v221, v221
	v_exp_f32_e32 v222, v222
	v_exp_f32_e32 v223, v223
	v_pk_mul_f32 v[88:89], v[92:93], v[88:89]
	v_pk_mul_f32 v[90:91], v[94:95], v[90:91]
	v_pk_mul_f32 v[80:81], v[84:85], v[80:81]
	v_pk_mul_f32 v[82:83], v[86:87], v[82:83]
	v_pk_add_f32 v[216:217], v[216:217], v[214:215]
	v_pk_add_f32 v[218:219], v[218:219], v[214:215]
	v_pk_add_f32 v[220:221], v[220:221], v[214:215]
	v_pk_add_f32 v[222:223], v[222:223], v[214:215]
	v_rcp_f32_e32 v216, v216
	v_rcp_f32_e32 v217, v217
	v_rcp_f32_e32 v218, v218
	v_rcp_f32_e32 v219, v219
	v_rcp_f32_e32 v220, v220
	v_rcp_f32_e32 v221, v221
	v_rcp_f32_e32 v222, v222
	v_rcp_f32_e32 v223, v223
	s_mov_b64 s[10:11], 0x2c000
	v_lshl_add_u64 v[208:209], v[210:211], 0, s[10:11]
	v_pk_mul_f32 v[88:89], v[88:89], v[216:217]
	v_pk_mul_f32 v[90:91], v[90:91], v[218:219]
	v_pk_mul_f32 v[80:81], v[80:81], v[220:221]
	v_pk_mul_f32 v[82:83], v[82:83], v[222:223]
	v_cvt_pk_bf16_f32 v92, v88, v89
	v_cvt_pk_bf16_f32 v93, v90, v91
	v_cvt_pk_bf16_f32 v94, v80, v81
	v_cvt_pk_bf16_f32 v95, v82, v83
	global_store_dwordx4 v[208:209], v[92:95], off
	v_pk_mul_f32 v[216:217], v[76:77], v[224:225]
	v_pk_mul_f32 v[218:219], v[78:79], v[224:225]
	v_pk_mul_f32 v[220:221], v[68:69], v[224:225]
	v_pk_mul_f32 v[222:223], v[70:71], v[224:225]
	v_exp_f32_e32 v216, v216
	v_exp_f32_e32 v217, v217
	v_exp_f32_e32 v218, v218
	v_exp_f32_e32 v219, v219
	v_exp_f32_e32 v220, v220
	v_exp_f32_e32 v221, v221
	v_exp_f32_e32 v222, v222
	v_exp_f32_e32 v223, v223
	v_pk_mul_f32 v[72:73], v[76:77], v[72:73]
	v_pk_mul_f32 v[74:75], v[78:79], v[74:75]
	v_pk_mul_f32 v[64:65], v[68:69], v[64:65]
	v_pk_mul_f32 v[66:67], v[70:71], v[66:67]
	v_pk_add_f32 v[216:217], v[216:217], v[214:215]
	v_pk_add_f32 v[218:219], v[218:219], v[214:215]
	v_pk_add_f32 v[220:221], v[220:221], v[214:215]
	v_pk_add_f32 v[222:223], v[222:223], v[214:215]
	v_rcp_f32_e32 v216, v216
	v_rcp_f32_e32 v217, v217
	v_rcp_f32_e32 v218, v218
	v_rcp_f32_e32 v219, v219
	v_rcp_f32_e32 v220, v220
	v_rcp_f32_e32 v221, v221
	v_rcp_f32_e32 v222, v222
	v_rcp_f32_e32 v223, v223
	s_mov_b64 s[10:11], 0x42000
	v_lshl_add_u64 v[208:209], v[210:211], 0, s[10:11]
	v_pk_mul_f32 v[72:73], v[72:73], v[216:217]
	v_pk_mul_f32 v[74:75], v[74:75], v[218:219]
	v_pk_mul_f32 v[64:65], v[64:65], v[220:221]
	v_pk_mul_f32 v[66:67], v[66:67], v[222:223]
	v_cvt_pk_bf16_f32 v76, v72, v73
	v_cvt_pk_bf16_f32 v77, v74, v75
	v_cvt_pk_bf16_f32 v78, v64, v65
	v_cvt_pk_bf16_f32 v79, v66, v67
	global_store_dwordx4 v[208:209], v[76:79], off
	v_pk_mul_f32 v[216:217], v[60:61], v[224:225]
	v_pk_mul_f32 v[218:219], v[62:63], v[224:225]
	v_pk_mul_f32 v[220:221], v[52:53], v[224:225]
	v_pk_mul_f32 v[222:223], v[54:55], v[224:225]
	v_exp_f32_e32 v216, v216
	v_exp_f32_e32 v217, v217
	v_exp_f32_e32 v218, v218
; __device__ __forceinline__ u32x4 pack8(const f32x4& a, const f32x4& b) { u32x4 w; w.x = pk2(a[0], a[1]); w.y = pk2(a[2], a[3]); w.z = pk2(b[0], b[1]); w.w = pk2(b[2], b[3]); return w; }
; __device__ __forceinline__ float sigm(float x) { return __builtin_amdgcn_rcpf(1.0f + __builtin_amdgcn_exp2f(x * -1.4426950408889634f)); }
;     __device__ __forceinline__ void operator()(const f32x4 (&acc)[2][2][4][2], const Unit& u, int wr, int wc, int fr, int fq) const {
;     ...
; #pragma unroll
;         for (int ai = 0; ai < 2; ++ai)
; #pragma unroll
;             for (int m = 0; m < 4; ++m) { f32x4 o[2];
; #pragma unroll
;                 for (int n = 0; n < 2; ++n) { const f32x4 a = acc[ai][0][m][n] * rx[ai][m], b = acc[ai][1][m][n] * rx[ai][m];
; #pragma unroll
;                     for (int e = 0; e < 4; ++e) o[n][e] = a[e] * sigm(a[e]) * b[e]; }
;                 *(u32x4*)(H + (size_t)(lrow0 + ai * HALF + m * 16) * DFF + col0) = pack8(o[0], o[1]); asm volatile("" ::: "memory"); }
	v_exp_f32_e32 v219, v219
	v_exp_f32_e32 v220, v220
	v_exp_f32_e32 v221, v221
	v_exp_f32_e32 v222, v222
	v_exp_f32_e32 v223, v223
	v_pk_mul_f32 v[56:57], v[60:61], v[56:57]
	v_pk_mul_f32 v[58:59], v[62:63], v[58:59]
	v_pk_mul_f32 v[48:49], v[52:53], v[48:49]
	v_pk_mul_f32 v[50:51], v[54:55], v[50:51]
	v_pk_add_f32 v[216:217], v[216:217], v[214:215]
	v_pk_add_f32 v[218:219], v[218:219], v[214:215]
	v_pk_add_f32 v[220:221], v[220:221], v[214:215]
	v_pk_add_f32 v[222:223], v[222:223], v[214:215]
	v_rcp_f32_e32 v216, v216
	v_rcp_f32_e32 v217, v217
	v_rcp_f32_e32 v218, v218
	v_rcp_f32_e32 v219, v219
	v_rcp_f32_e32 v220, v220
	v_rcp_f32_e32 v221, v221
	v_rcp_f32_e32 v222, v222
	v_rcp_f32_e32 v223, v223
	s_mov_b64 s[10:11], 0xb0000
	v_lshl_add_u64 v[208:209], v[210:211], 0, s[10:11]
	v_pk_mul_f32 v[56:57], v[56:57], v[216:217]
	v_pk_mul_f32 v[58:59], v[58:59], v[218:219]
	v_pk_mul_f32 v[48:49], v[48:49], v[220:221]
	v_pk_mul_f32 v[50:51], v[50:51], v[222:223]
	v_cvt_pk_bf16_f32 v60, v56, v57
	v_cvt_pk_bf16_f32 v61, v58, v59
	v_cvt_pk_bf16_f32 v62, v48, v49
	v_cvt_pk_bf16_f32 v63, v50, v51
	global_store_dwordx4 v[208:209], v[60:63], off
	v_pk_mul_f32 v[216:217], v[44:45], v[224:225]
	v_pk_mul_f32 v[218:219], v[46:47], v[224:225]
	v_pk_mul_f32 v[220:221], v[36:37], v[224:225]
	v_pk_mul_f32 v[222:223], v[38:39], v[224:225]
	v_exp_f32_e32 v216, v216
	v_exp_f32_e32 v217, v217
	v_exp_f32_e32 v218, v218
	v_exp_f32_e32 v219, v219
	v_exp_f32_e32 v220, v220
	v_exp_f32_e32 v221, v221
	v_exp_f32_e32 v222, v222
	v_exp_f32_e32 v223, v223
	v_pk_mul_f32 v[40:41], v[44:45], v[40:41]
	v_pk_mul_f32 v[42:43], v[46:47], v[42:43]
	v_pk_mul_f32 v[32:33], v[36:37], v[32:33]
	v_pk_mul_f32 v[34:35], v[38:39], v[34:35]
	v_pk_add_f32 v[216:217], v[216:217], v[214:215]
	v_pk_add_f32 v[218:219], v[218:219], v[214:215]
	v_pk_add_f32 v[220:221], v[220:221], v[214:215]
	v_pk_add_f32 v[222:223], v[222:223], v[214:215]
	v_rcp_f32_e32 v216, v216
	v_rcp_f32_e32 v217, v217
	v_rcp_f32_e32 v218, v218
	v_rcp_f32_e32 v219, v219
	v_rcp_f32_e32 v220, v220
	v_rcp_f32_e32 v221, v221
	v_rcp_f32_e32 v222, v222
	v_rcp_f32_e32 v223, v223
	s_mov_b64 s[10:11], 0xc6000
	v_lshl_add_u64 v[208:209], v[210:211], 0, s[10:11]
	v_pk_mul_f32 v[40:41], v[40:41], v[216:217]
	v_pk_mul_f32 v[42:43], v[42:43], v[218:219]
	v_pk_mul_f32 v[32:33], v[32:33], v[220:221]
	v_pk_mul_f32 v[34:35], v[34:35], v[222:223]
	v_cvt_pk_bf16_f32 v44, v40, v41
	v_cvt_pk_bf16_f32 v45, v42, v43
	v_cvt_pk_bf16_f32 v46, v32, v33
	v_cvt_pk_bf16_f32 v47, v34, v35
	global_store_dwordx4 v[208:209], v[44:47], off
	v_pk_mul_f32 v[216:217], v[28:29], v[224:225]
	v_pk_mul_f32 v[218:219], v[30:31], v[224:225]
	v_pk_mul_f32 v[220:221], v[20:21], v[224:225]
	v_pk_mul_f32 v[222:223], v[22:23], v[224:225]
	v_exp_f32_e32 v216, v216
	v_exp_f32_e32 v217, v217
	v_exp_f32_e32 v218, v218
	v_exp_f32_e32 v219, v219
	v_exp_f32_e32 v220, v220
	v_exp_f32_e32 v221, v221
	v_exp_f32_e32 v222, v222
	v_exp_f32_e32 v223, v223
	v_pk_mul_f32 v[24:25], v[28:29], v[24:25]
	v_pk_mul_f32 v[26:27], v[30:31], v[26:27]
	v_pk_mul_f32 v[16:17], v[20:21], v[16:17]
	v_pk_mul_f32 v[18:19], v[22:23], v[18:19]
	v_pk_add_f32 v[216:217], v[216:217], v[214:215]
	v_pk_add_f32 v[218:219], v[218:219], v[214:215]
	v_pk_add_f32 v[220:221], v[220:221], v[214:215]
	v_pk_add_f32 v[222:223], v[222:223], v[214:215]
	v_rcp_f32_e32 v216, v216
	v_rcp_f32_e32 v217, v217
	v_rcp_f32_e32 v218, v218
	v_rcp_f32_e32 v219, v219
	v_rcp_f32_e32 v220, v220
	v_rcp_f32_e32 v221, v221
	v_rcp_f32_e32 v222, v222
	v_rcp_f32_e32 v223, v223
	s_mov_b64 s[10:11], 0xdc000
	v_lshl_add_u64 v[208:209], v[210:211], 0, s[10:11]
	v_pk_mul_f32 v[24:25], v[24:25], v[216:217]
	v_pk_mul_f32 v[26:27], v[26:27], v[218:219]
	v_pk_mul_f32 v[16:17], v[16:17], v[220:221]
	v_pk_mul_f32 v[18:19], v[18:19], v[222:223]
	v_cvt_pk_bf16_f32 v28, v24, v25
	v_cvt_pk_bf16_f32 v29, v26, v27
	v_cvt_pk_bf16_f32 v30, v16, v17
	v_cvt_pk_bf16_f32 v31, v18, v19
	global_store_dwordx4 v[208:209], v[28:31], off
	v_pk_mul_f32 v[216:217], v[12:13], v[224:225]
	v_pk_mul_f32 v[218:219], v[14:15], v[224:225]
	v_pk_mul_f32 v[220:221], v[4:5], v[224:225]
	v_pk_mul_f32 v[222:223], v[6:7], v[224:225]
	v_exp_f32_e32 v216, v216
	v_exp_f32_e32 v217, v217
	v_exp_f32_e32 v218, v218
	v_exp_f32_e32 v219, v219
	v_exp_f32_e32 v220, v220
	v_exp_f32_e32 v221, v221
	v_exp_f32_e32 v222, v222
	v_exp_f32_e32 v223, v223
	v_pk_mul_f32 v[8:9], v[12:13], v[8:9]
	v_pk_mul_f32 v[10:11], v[14:15], v[10:11]
	v_pk_mul_f32 v[0:1], v[4:5], v[0:1]
	v_pk_mul_f32 v[2:3], v[6:7], v[2:3]
	v_pk_add_f32 v[216:217], v[216:217], v[214:215]
	v_pk_add_f32 v[218:219], v[218:219], v[214:215]
	v_pk_add_f32 v[220:221], v[220:221], v[214:215]
	v_pk_add_f32 v[222:223], v[222:223], v[214:215]
	v_rcp_f32_e32 v216, v216
	v_rcp_f32_e32 v217, v217
	v_rcp_f32_e32 v218, v218
	v_rcp_f32_e32 v219, v219
	v_rcp_f32_e32 v220, v220
	v_rcp_f32_e32 v221, v221
	v_rcp_f32_e32 v222, v222
	v_rcp_f32_e32 v223, v223
	s_mov_b64 s[10:11], 0xf2000
	v_lshl_add_u64 v[208:209], v[210:211], 0, s[10:11]
	v_pk_mul_f32 v[8:9], v[8:9], v[216:217]
	v_pk_mul_f32 v[10:11], v[10:11], v[218:219]
	v_pk_mul_f32 v[0:1], v[0:1], v[220:221]
	v_pk_mul_f32 v[2:3], v[2:3], v[222:223]
	v_cvt_pk_bf16_f32 v12, v8, v9
	v_cvt_pk_bf16_f32 v13, v10, v11
	v_cvt_pk_bf16_f32 v14, v0, v1
	v_cvt_pk_bf16_f32 v15, v2, v3
	global_store_dwordx4 v[208:209], v[12:15], off
	s_andn2_b64 vcc, exec, s[40:41]
	s_cbranch_vccnz .LBB0_573
	s_andn2_b64 vcc, exec, s[22:23]
	s_cbranch_vccnz .LBB0_572
	s_barrier
	s_branch .LBB0_572
